# memory cross-attention units dealt statically (unit = vcu + G*k) instead of the atomic work queue: no device atomic and two fewer workgroup barriers per unit
# speedup vs baseline: 1.0047x; 1.0032x over previous
.LBB0_59:
	v_readlane_b32 s98, v255, 14
	v_readlane_b32 s99, v254, 4
	s_lshl_b32 s6, s16, 2
	s_waitcnt lgkmcnt(0)
	s_add_u32 s6, s74, s6
	s_addc_u32 s7, s75, 0
	s_add_u32 s6, s6, 0x3840
	s_addc_u32 s7, s7, 0
	s_add_u32 s11, s74, 0x23400000
	s_addc_u32 s24, s75, 0
	s_lshl_b32 s8, s16, 11
	s_add_u32 s8, s74, s8
	s_addc_u32 s9, s75, 0
	s_add_u32 s25, s8, 0x9400000
	s_mov_b32 s92, 0x54442d18
	s_movk_i32 s64, 0xe7f0
	v_readlane_b32 s48, v255, 49
	s_addc_u32 s30, s9, 0
	s_mov_b32 s93, 0xbff921fb
	v_readlane_b32 s66, v255, 46
	v_readlane_b32 s51, v255, 47
	s_movk_i32 s67, 0x2000
	s_mov_b32 s71, 0x10000
	s_movk_i32 s54, 0x1000
	s_mov_b32 s65, -1
	v_readlane_b32 s72, v255, 52
	v_readlane_b32 s50, v255, 51
	v_readlane_b32 s49, v255, 50
	v_mov_b64_e32 v[234:235], 0x3ff
	v_mov_b32_e32 v236, v209
	v_mov_b32_e32 v209, v212
	v_mov_b32_e32 v212, 0x2490
	v_mov_b32_e32 v237, 0x28a0
	s_branch .LBB0_62

.LBB0_62:
	s_mov_b32 s8, s98
	s_add_i32 s98, s98, s99
	s_mov_b64 s[12:13], -1
	s_cmpk_gt_i32 s8, 0x1ff
	s_cbranch_scc1 .LBB0_61
	s_ashr_i32 s12, s8, 6
	s_ashr_i32 s13, s12, 31
	s_lshl_b32 s9, s8, 8
	s_lshl_b64 s[14:15], s[12:13], 12
	s_and_b32 s9, s9, 0xf00
	s_or_b32 s14, s14, s9
	s_mul_i32 s9, s15, 0x2800
	s_mul_hi_u32 s20, s14, 0x2800
	s_add_i32 s20, s20, s9
	s_mul_i32 s9, s14, 0x2800
	s_add_u32 s36, s11, s9
	s_addc_u32 s37, s24, s20
	s_lshl_b32 s8, s8, 3
	s_and_b32 s8, s8, 0x180
	s_lshl_b32 s35, s8, 1
	s_add_u32 s8, s36, s35
	s_addc_u32 s9, s37, 0
	s_add_u32 s8, s8, 0x1400
	s_addc_u32 s9, s9, 0
	s_lshl_b64 s[12:13], s[12:13], 21
	s_add_u32 s12, s25, s12
	s_addc_u32 s13, s30, s13
	v_mov_b32_e32 v38, v203
	s_add_u32 s12, s12, s35
	s_addc_u32 s13, s13, 0
	v_readfirstlane_b32 s20, v38
	s_ashr_i32 s34, s20, 6
	v_and_b32_e32 v39, 31, v38
	s_lshl_b32 s31, s34, 5
	v_or_b32_e32 v2, s31, v39
	v_mov_b64_e32 v[0:1], s[8:9]
	v_mad_i64_i32 v[0:1], s[8:9], v2, s90, v[0:1]
	v_lshrrev_b32_e32 v2, 1, v38
	v_and_b32_e32 v184, 16, v2
	v_lshl_add_u64 v[0:1], v[0:1], 0, v[184:185]
	global_load_dwordx4 v[124:127], v[0:1], off
	global_load_dwordx4 v[120:123], v[0:1], off offset:32
	global_load_dwordx4 v[116:119], v[0:1], off offset:64
	global_load_dwordx4 v[112:115], v[0:1], off offset:96
	global_load_dwordx4 v[108:111], v[0:1], off offset:128
	global_load_dwordx4 v[104:107], v[0:1], off offset:160
	global_load_dwordx4 v[100:103], v[0:1], off offset:192
	global_load_dwordx4 v[96:99], v[0:1], off offset:224
	s_lshl_b32 s8, s34, 3
	v_bfe_u32 v3, v38, 4, 2
	v_bfe_u32 v0, v38, 2, 3
	v_and_b32_e32 v1, 8, v2
	s_lshl_b32 s9, s34, 2
	v_or_b32_e32 v2, s8, v3
	v_bitop3_b32 v0, s8, -13, v0 bitop3:0xc8
	s_and_b32 s9, s9, 4
	v_bitop3_b32 v6, s8, v38, v3 bitop3:0x36
	v_ashrrev_i32_e32 v3, 31, v2
	v_or3_b32 v0, v0, v1, s9
	v_lshlrev_b64 v[4:5], 13, v[2:3]
	v_lshlrev_b32_e32 v3, 4, v6
	v_lshlrev_b32_e32 v8, 3, v38
	v_ashrrev_i32_e32 v1, 31, v0
	v_and_b32_e32 v6, 0xf0, v3
	v_and_b32_e32 v3, 32, v38
	v_lshlrev_b64 v[0:1], 13, v[0:1]
	v_lshl_add_u64 v[4:5], s[12:13], 0, v[4:5]
	v_mov_b32_e32 v7, v185
	v_and_or_b32 v3, v8, 24, v3
	s_and_b32 s20, s20, 0x3fffffc0
	v_lshl_add_u64 v[0:1], s[12:13], 0, v[0:1]
	v_lshl_add_u64 v[132:133], v[4:5], 0, v[6:7]
	v_lshlrev_b32_e32 v4, 1, v3
	v_mov_b32_e32 v5, v185
	s_lshl_b32 s20, s20, 2
	v_lshl_add_u64 v[36:37], v[0:1], 0, v[4:5]
	v_or_b32_e32 v0, 4, v2
	s_add_i32 s38, s20, 0
	v_bitop3_b32 v2, v2, v38, 4 bitop3:0x36
	v_ashrrev_i32_e32 v1, 31, v0
	s_add_i32 s38, s38, 0x18000
	s_mov_b64 s[8:9], 0x400
	v_lshlrev_b64 v[0:1], 13, v[0:1]
	v_lshlrev_b32_e32 v2, 4, v2
	v_lshl_add_u64 v[128:129], v[36:37], 0, s[8:9]
	v_lshl_add_u64 v[0:1], s[12:13], 0, v[0:1]
	v_and_b32_e32 v2, 0xf0, v2
	v_mov_b32_e32 v3, v185
	s_mov_b64 s[8:9], 0x480
	s_cmp_lg_u32 0, -1
	v_lshl_add_u64 v[130:131], v[0:1], 0, v[2:3]
	v_lshl_add_u64 v[0:1], v[36:37], 0, s[8:9]
	s_cselect_b32 s12, 0, 0
	s_lshl_b32 s9, s34, 11
	s_add_i32 s8, s9, s12
	s_add_i32 s13, s8, 0xc000
	s_mov_b32 m0, s13
	s_add_i32 s33, s8, 0xc400
	global_load_lds_dwordx4 v[132:133], off
	s_mov_b32 m0, s33
	s_or_b32 s39, s9, 0x400
	global_load_lds_dwordx4 v[130:131], off
	s_mov_b32 m0, s8
	s_add_i32 s47, s8, 0x10000
	global_load_lds_dwordx4 v[128:129], off
	s_add_i32 m0, s39, s12
	s_add_i32 s46, s8, 0x10400
	global_load_lds_dwordx4 v[0:1], off
	v_lshl_add_u64 v[0:1], v[132:133], 0, s[22:23]
	s_mov_b32 m0, s47
	s_mov_b64 s[20:21], 0x80400
	global_load_lds_dwordx4 v[0:1], off
	v_lshl_add_u64 v[0:1], v[130:131], 0, s[22:23]
	s_mov_b32 m0, s46
	v_lshlrev_b32_e32 v40, 4, v38
	global_load_lds_dwordx4 v[0:1], off
	v_lshl_add_u64 v[0:1], v[36:37], 0, s[20:21]
	s_add_i32 m0, s8, 0x4000
	s_mov_b64 s[20:21], 0x80480
	global_load_lds_dwordx4 v[0:1], off
	v_lshl_add_u64 v[0:1], v[36:37], 0, s[20:21]
	s_add_i32 m0, s8, 0x4400
	v_lshlrev_b32_e32 v41, 8, v39
	v_and_b32_e32 v42, 0xf0, v40
	global_load_lds_dwordx4 v[0:1], off
	v_bitop3_b32 v43, v184, v41, v42 bitop3:0xde
	s_waitcnt vmcnt(0) lgkmcnt(0)
	s_barrier
	v_add_u32_e32 v151, 0, v43
	ds_read_b128 v[0:3], v151 offset:49152
	v_or_b32_e32 v32, 32, v184
	v_bitop3_b32 v44, v32, v41, v42 bitop3:0xde
	v_add_u32_e32 v156, 0, v44
	ds_read_b128 v[32:35], v156 offset:49152
	s_waitcnt vmcnt(0) lgkmcnt(0)
	v_mfma_f32_32x32x16_bf16 v[16:31], v[0:3], v[124:127], 0
	ds_read_b128 v[0:3], v151 offset:57344
	s_mov_b32 s44, 0x42b504f3
	s_mov_b64 s[20:21], 0x100000
	s_mov_b32 m0, s13
	v_and_b32_e32 v134, 63, v38
	v_cmp_gt_u32_e64 s[42:43], 32, v134
	v_lshl_add_u32 v136, v39, 2, s38
	v_mfma_f32_32x32x16_bf16 v[16:31], v[32:35], v[120:123], v[16:31]
	ds_read_b128 v[32:35], v156 offset:57344
	s_waitcnt lgkmcnt(1)
	v_mfma_f32_32x32x16_bf16 v[0:15], v[0:3], v[124:127], 0
	s_waitcnt lgkmcnt(0)
	v_mfma_f32_32x32x16_bf16 v[0:15], v[32:35], v[120:123], v[0:15]
	v_or_b32_e32 v32, 64, v184
	v_bitop3_b32 v45, v32, v41, v42 bitop3:0xde
	v_add_u32_e32 v157, 0, v45
	ds_read_b128 v[32:35], v157 offset:49152
	s_waitcnt lgkmcnt(0)
	v_mfma_f32_32x32x16_bf16 v[16:31], v[32:35], v[116:119], v[16:31]
	ds_read_b128 v[32:35], v157 offset:57344
	s_waitcnt lgkmcnt(0)
	v_mfma_f32_32x32x16_bf16 v[0:15], v[32:35], v[116:119], v[0:15]
	v_or_b32_e32 v32, 0x60, v184
	v_bitop3_b32 v46, v32, v41, v42 bitop3:0xde
	v_add_u32_e32 v152, 0, v46
	ds_read_b128 v[32:35], v152 offset:49152
	s_waitcnt lgkmcnt(0)
	v_mfma_f32_32x32x16_bf16 v[16:31], v[32:35], v[112:115], v[16:31]
	ds_read_b128 v[32:35], v152 offset:57344
	s_waitcnt lgkmcnt(0)
	v_mfma_f32_32x32x16_bf16 v[0:15], v[32:35], v[112:115], v[0:15]
	v_or_b32_e32 v32, 0x80, v184
	v_bitop3_b32 v47, v32, v41, v42 bitop3:0xde
	v_add_u32_e32 v153, 0, v47
	ds_read_b128 v[32:35], v153 offset:49152
	s_waitcnt lgkmcnt(0)
	v_mfma_f32_32x32x16_bf16 v[16:31], v[32:35], v[108:111], v[16:31]
	ds_read_b128 v[32:35], v153 offset:57344
	s_waitcnt lgkmcnt(0)
	v_mfma_f32_32x32x16_bf16 v[0:15], v[32:35], v[108:111], v[0:15]
	v_or_b32_e32 v32, 0xa0, v184
	v_bitop3_b32 v48, v32, v41, v42 bitop3:0xde
	v_add_u32_e32 v154, 0, v48
	ds_read_b128 v[32:35], v154 offset:49152
	s_waitcnt lgkmcnt(0)
	v_mfma_f32_32x32x16_bf16 v[16:31], v[32:35], v[104:107], v[16:31]
	ds_read_b128 v[32:35], v154 offset:57344
	s_waitcnt lgkmcnt(0)
	v_mfma_f32_32x32x16_bf16 v[0:15], v[32:35], v[104:107], v[0:15]
	v_or_b32_e32 v32, 0xc0, v184
	v_bitop3_b32 v49, v32, v41, v42 bitop3:0xde
	v_add_u32_e32 v155, 0, v49
	ds_read_b128 v[32:35], v155 offset:49152
	s_waitcnt lgkmcnt(0)
	v_mfma_f32_32x32x16_bf16 v[16:31], v[32:35], v[100:103], v[16:31]
	ds_read_b128 v[32:35], v155 offset:57344
	s_waitcnt lgkmcnt(0)
	v_mfma_f32_32x32x16_bf16 v[0:15], v[32:35], v[100:103], v[0:15]
	v_or_b32_e32 v32, 0xe0, v184
	v_bitop3_b32 v41, v32, v41, v42 bitop3:0xde
	v_add_u32_e32 v150, 0, v41
	ds_read_b128 v[32:35], v150 offset:49152
	s_waitcnt lgkmcnt(0)
	v_mfma_f32_32x32x16_bf16 v[16:31], v[32:35], v[96:99], v[16:31]
	ds_read_b128 v[32:35], v150 offset:57344
	s_waitcnt vmcnt(0) lgkmcnt(0)
	s_barrier
	s_waitcnt lgkmcnt(0)
	v_mfma_f32_32x32x16_bf16 v[0:15], v[32:35], v[96:99], v[0:15]
	s_nop 8
	v_max_f32_e32 v32, v17, v17
	v_max_f32_e32 v33, v16, v16
	v_max_f32_e32 v32, v33, v32
	v_max3_f32 v32, v32, v18, v19
	v_max3_f32 v32, v32, v20, v21
	v_max3_f32 v32, v32, v22, v23
	v_max3_f32 v32, v32, v24, v25
	v_max3_f32 v32, v32, v26, v27
	v_max3_f32 v32, v32, v28, v29
	v_max3_f32 v32, v32, v30, v31
	v_max3_f32 v32, v32, v0, v1
	v_max3_f32 v32, v32, v2, v3
	v_max3_f32 v32, v32, v4, v5
	v_max3_f32 v32, v32, v6, v7
	v_max3_f32 v32, v32, v8, v9
	v_max3_f32 v32, v32, v10, v11
	v_max3_f32 v32, v32, v12, v13
	v_max3_f32 v32, v32, v14, v15
	v_mov_b32_e32 v33, v32
	s_nop 1
	v_permlane32_swap_b32_e32 v32, v33
	v_max_f32_e32 v33, v33, v33
	v_max_f32_e32 v32, v32, v32
	v_max_f32_e32 v34, v32, v33
	v_add_f32_e32 v32, 0x7149f2ca, v34
	v_cmp_ge_f32_e32 vcc, s44, v32
	v_lshl_add_u64 v[32:33], v[132:133], 0, s[20:21]
	s_cmp_eq_u64 vcc, exec
	global_load_lds_dwordx4 v[32:33], off
	v_lshl_add_u64 v[32:33], v[130:131], 0, s[20:21]
	s_mov_b32 m0, s33
	s_mov_b64 s[20:21], 0x100400
	s_cselect_b64 s[40:41], -1, 0
	global_load_lds_dwordx4 v[32:33], off
	v_lshl_add_u64 v[32:33], v[36:37], 0, s[20:21]
	s_add_i32 m0, s8, 0x8000
	s_mov_b64 s[20:21], 0x100480
	global_load_lds_dwordx4 v[32:33], off
	v_lshl_add_u64 v[32:33], v[36:37], 0, s[20:21]
	s_add_i32 m0, s8, 0x8400
	v_max_f32_e32 v135, 0xf149f2ca, v34
	global_load_lds_dwordx4 v[32:33], off
	v_lshlrev_b32_e32 v32, 3, v134
	v_and_b32_e32 v33, 0xc0, v40
	v_lshlrev_b32_e32 v34, 1, v38
	v_and_or_b32 v33, v32, 24, v33
	v_and_b32_e32 v34, 32, v34
	v_and_b32_e32 v32, 0x100, v32
	v_cndmask_b32_e64 v158, v135, v207, s[40:41]
	v_or3_b32 v141, v33, v34, v32
	v_mul_f32_e32 v32, 0xbe0293ee, v158
	v_fmamk_f32 v16, v16, 0x3e0293ee, v32
	v_fmamk_f32 v17, v17, 0x3e0293ee, v32
	v_fmamk_f32 v18, v18, 0x3e0293ee, v32
	v_fmamk_f32 v19, v19, 0x3e0293ee, v32
	v_fmamk_f32 v20, v20, 0x3e0293ee, v32
	v_fmamk_f32 v21, v21, 0x3e0293ee, v32
	v_fmamk_f32 v22, v22, 0x3e0293ee, v32
	v_fmamk_f32 v23, v23, 0x3e0293ee, v32
	v_fmamk_f32 v24, v24, 0x3e0293ee, v32
	v_fmamk_f32 v25, v25, 0x3e0293ee, v32
	v_fmamk_f32 v26, v26, 0x3e0293ee, v32
	v_fmamk_f32 v27, v27, 0x3e0293ee, v32
	v_fmamk_f32 v28, v28, 0x3e0293ee, v32
	v_fmamk_f32 v29, v29, 0x3e0293ee, v32
	v_fmamk_f32 v30, v30, 0x3e0293ee, v32
	v_fmamk_f32 v31, v31, 0x3e0293ee, v32
	v_fmamk_f32 v33, v0, 0x3e0293ee, v32
	v_fmamk_f32 v34, v1, 0x3e0293ee, v32
	v_fmamk_f32 v35, v2, 0x3e0293ee, v32
	v_fmamk_f32 v36, v3, 0x3e0293ee, v32
	v_fmamk_f32 v37, v4, 0x3e0293ee, v32
	v_fmamk_f32 v38, v5, 0x3e0293ee, v32
	v_fmamk_f32 v40, v6, 0x3e0293ee, v32
	v_fmamk_f32 v42, v7, 0x3e0293ee, v32
	v_fmamk_f32 v8, v8, 0x3e0293ee, v32
	v_fmamk_f32 v9, v9, 0x3e0293ee, v32
	v_fmamk_f32 v10, v10, 0x3e0293ee, v32
	v_fmamk_f32 v11, v11, 0x3e0293ee, v32
	v_fmamk_f32 v12, v12, 0x3e0293ee, v32
	v_fmamk_f32 v13, v13, 0x3e0293ee, v32
	v_fmamk_f32 v14, v14, 0x3e0293ee, v32
	v_fmac_f32_e32 v32, 0x3e0293ee, v15
	v_exp_f32_e32 v15, v16
	v_exp_f32_e32 v16, v17
	v_exp_f32_e32 v17, v18
	v_exp_f32_e32 v18, v19
	v_exp_f32_e32 v19, v20
	v_exp_f32_e32 v20, v21
	v_exp_f32_e32 v21, v22
	v_exp_f32_e32 v22, v23
	v_exp_f32_e32 v23, v24
	v_exp_f32_e32 v24, v25
	v_exp_f32_e32 v25, v26
	v_exp_f32_e32 v26, v27
	v_exp_f32_e32 v27, v28
	v_exp_f32_e32 v28, v29
	v_exp_f32_e32 v29, v30
	v_exp_f32_e32 v30, v31
	s_add_i32 s8, 0, 0x10000
	v_add_u32_e32 v137, s12, v141
	v_add_u32_e32 v149, s8, v43
	v_add_u32_e32 v148, s8, v44
	v_add_u32_e32 v147, s8, v45
	v_add_u32_e32 v146, s8, v46
	v_add_u32_e32 v145, s8, v47
	v_add_u32_e32 v144, s8, v48
	v_add_u32_e32 v143, s8, v49
	v_add_u32_e32 v142, s8, v41
	ds_read_b128 v[0:3], v149
	ds_read_b128 v[4:7], v149 offset:8192
	v_exp_f32_e32 v31, v32
	v_add_f32_e32 v32, 0, v15
	v_add_f32_e32 v32, v16, v32
	s_waitcnt lgkmcnt(0)
	v_mfma_f32_32x32x16_bf16 v[80:95], v[0:3], v[124:127], 0
	v_add_f32_e32 v32, v17, v32
	v_add_f32_e32 v32, v18, v32
	v_add_f32_e32 v32, v19, v32
	v_add_f32_e32 v32, v20, v32
	v_add_f32_e32 v32, v21, v32
	v_add_f32_e32 v32, v22, v32
	v_add_f32_e32 v32, v23, v32
	v_mfma_f32_32x32x16_bf16 v[64:79], v[4:7], v[124:127], 0
	ds_read_b128 v[0:3], v148
	ds_read_b128 v[4:7], v148 offset:8192
	v_add_f32_e32 v32, v24, v32
	v_add_f32_e32 v32, v25, v32
	v_add_f32_e32 v32, v26, v32
	v_add_f32_e32 v32, v27, v32
	v_add_f32_e32 v32, v28, v32
	v_add_f32_e32 v32, v29, v32
	s_waitcnt lgkmcnt(0)
	v_mfma_f32_32x32x16_bf16 v[80:95], v[0:3], v[120:123], v[80:95]
	v_add_f32_e32 v32, v30, v32
	v_exp_f32_e32 v8, v8
	v_exp_f32_e32 v9, v9
	v_exp_f32_e32 v10, v10
	v_exp_f32_e32 v11, v11
	v_exp_f32_e32 v12, v12
	v_exp_f32_e32 v13, v13
	v_mfma_f32_32x32x16_bf16 v[64:79], v[4:7], v[120:123], v[64:79]
	ds_read_b128 v[0:3], v147
	ds_read_b128 v[4:7], v147 offset:8192
	v_exp_f32_e32 v14, v14
	s_waitcnt lgkmcnt(0)
	v_mfma_f32_32x32x16_bf16 v[80:95], v[0:3], v[116:119], v[80:95]
	v_mfma_f32_32x32x16_bf16 v[64:79], v[4:7], v[116:119], v[64:79]
	ds_read_b128 v[0:3], v146
	ds_read_b128 v[4:7], v146 offset:8192
	s_waitcnt lgkmcnt(0)
	v_mfma_f32_32x32x16_bf16 v[80:95], v[0:3], v[112:115], v[80:95]
	v_mfma_f32_32x32x16_bf16 v[64:79], v[4:7], v[112:115], v[64:79]
	ds_read_b128 v[0:3], v145
	ds_read_b128 v[4:7], v145 offset:8192
	s_waitcnt lgkmcnt(0)
	v_mfma_f32_32x32x16_bf16 v[80:95], v[0:3], v[108:111], v[80:95]
	v_mfma_f32_32x32x16_bf16 v[64:79], v[4:7], v[108:111], v[64:79]
	ds_read_b128 v[0:3], v144
	ds_read_b128 v[4:7], v144 offset:8192
	s_waitcnt lgkmcnt(0)
	v_mfma_f32_32x32x16_bf16 v[80:95], v[0:3], v[104:107], v[80:95]
	v_mfma_f32_32x32x16_bf16 v[64:79], v[4:7], v[104:107], v[64:79]
	ds_read_b128 v[0:3], v143
	ds_read_b128 v[4:7], v143 offset:8192
	s_waitcnt lgkmcnt(0)
	v_mfma_f32_32x32x16_bf16 v[80:95], v[0:3], v[100:103], v[80:95]
	v_mfma_f32_32x32x16_bf16 v[64:79], v[4:7], v[100:103], v[64:79]
	ds_read_b128 v[0:3], v142
	ds_read_b128 v[4:7], v142 offset:8192
	v_cvt_pk_bf16_f32 v48, v15, v16
	v_cvt_pk_bf16_f32 v49, v17, v18
	v_cvt_pk_bf16_f32 v50, v19, v20
	v_cvt_pk_bf16_f32 v51, v21, v22
	v_cvt_pk_bf16_f32 v160, v23, v24
	v_cvt_pk_bf16_f32 v161, v25, v26
	s_waitcnt lgkmcnt(0)
	v_mfma_f32_32x32x16_bf16 v[80:95], v[0:3], v[96:99], v[80:95]
	v_exp_f32_e32 v0, v33
	v_exp_f32_e32 v1, v34
	v_exp_f32_e32 v2, v35
	v_exp_f32_e32 v3, v36
	v_add_f32_e32 v32, v0, v32
	v_add_f32_e32 v32, v1, v32
	v_add_f32_e32 v32, v2, v32
	v_mfma_f32_32x32x16_bf16 v[64:79], v[4:7], v[96:99], v[64:79]
	v_exp_f32_e32 v4, v37
	v_exp_f32_e32 v5, v38
	v_exp_f32_e32 v6, v40
	v_exp_f32_e32 v7, v42
	v_add_f32_e32 v32, v3, v32
	v_add_f32_e32 v32, v4, v32
	v_add_f32_e32 v32, v5, v32
	v_add_f32_e32 v32, v6, v32
	v_add_f32_e32 v32, v7, v32
	v_add_f32_e32 v32, v8, v32
	v_add_f32_e32 v32, v9, v32
	v_add_f32_e32 v32, v10, v32
	v_add_f32_e32 v32, v11, v32
	v_add_f32_e32 v32, v12, v32
	v_add_f32_e32 v32, v13, v32
	v_add_f32_e32 v32, v14, v32
	v_add_f32_e32 v138, v31, v32
	v_mov_b32_e32 v139, v138
	s_nop 1
	v_permlane32_swap_b32_e32 v138, v139
	v_permlane32_swap_b32_e32 v48, v50
	v_permlane32_swap_b32_e32 v49, v51
	v_cvt_pk_bf16_f32 v162, v27, v28
	v_cvt_pk_bf16_f32 v163, v29, v30
	v_cvt_pk_bf16_f32 v164, v0, v1
	v_cvt_pk_bf16_f32 v165, v2, v3
	v_cvt_pk_bf16_f32 v166, v4, v5
	v_cvt_pk_bf16_f32 v167, v6, v7
	v_cvt_pk_bf16_f32 v168, v8, v9
	v_cvt_pk_bf16_f32 v169, v10, v11
	v_cvt_pk_bf16_f32 v170, v12, v13
	v_cvt_pk_bf16_f32 v171, v14, v31
	s_nop 0
	v_permlane32_swap_b32_e32 v160, v162
	v_permlane32_swap_b32_e32 v161, v163
	v_permlane32_swap_b32_e32 v164, v166
	v_permlane32_swap_b32_e32 v165, v167
	v_permlane32_swap_b32_e32 v168, v170
	v_permlane32_swap_b32_e32 v169, v171
	ds_read_b64_tr_b16 v[0:1], v137 offset:0
	ds_read_b64_tr_b16 v[2:3], v137 offset:0x800
	ds_read_b64_tr_b16 v[16:17], v137 offset:0x1000
	ds_read_b64_tr_b16 v[18:19], v137 offset:0x1800
	ds_read_b64_tr_b16 v[20:21], v137 offset:0x2000
	ds_read_b64_tr_b16 v[22:23], v137 offset:0x2800
	ds_read_b64_tr_b16 v[24:25], v137 offset:0x3000
	ds_read_b64_tr_b16 v[26:27], v137 offset:0x3800
	s_nop 0
	s_waitcnt lgkmcnt(6)
	s_nop 0
	v_mfma_f32_32x32x16_bf16 v[0:15], v[48:51], v[0:3], 0
	s_waitcnt lgkmcnt(4)
	s_nop 0
	v_mfma_f32_32x32x16_bf16 v[0:15], v[160:163], v[16:19], v[0:15]
	s_waitcnt lgkmcnt(2)
	s_nop 0
	v_mfma_f32_32x32x16_bf16 v[0:15], v[164:167], v[20:23], v[0:15]
	s_waitcnt lgkmcnt(0)
	ds_read_b64_tr_b16 v[16:17], v137 offset:0x200
	ds_read_b64_tr_b16 v[18:19], v137 offset:0xa00
	ds_read_b64_tr_b16 v[32:33], v137 offset:0x1200
	ds_read_b64_tr_b16 v[34:35], v137 offset:0x1a00
	s_nop 0
	v_mfma_f32_32x32x16_bf16 v[0:15], v[168:171], v[24:27], v[0:15]
	ds_read_b64_tr_b16 v[36:37], v137 offset:0x2200
	ds_read_b64_tr_b16 v[38:39], v137 offset:0x2a00
	ds_read_b64_tr_b16 v[40:41], v137 offset:0x3200
	ds_read_b64_tr_b16 v[42:43], v137 offset:0x3a00
	s_waitcnt lgkmcnt(6)
	s_nop 0
	v_mfma_f32_32x32x16_bf16 v[16:31], v[48:51], v[16:19], 0
	s_waitcnt lgkmcnt(4)
	s_nop 0
	v_mfma_f32_32x32x16_bf16 v[16:31], v[160:163], v[32:35], v[16:31]
	s_waitcnt lgkmcnt(2)
	s_nop 0
	v_mfma_f32_32x32x16_bf16 v[16:31], v[164:167], v[36:39], v[16:31]
	s_waitcnt lgkmcnt(0)
	ds_read_b64_tr_b16 v[32:33], v137 offset:0x400
	ds_read_b64_tr_b16 v[34:35], v137 offset:0xc00
	ds_read_b64_tr_b16 v[52:53], v137 offset:0x1400
	ds_read_b64_tr_b16 v[54:55], v137 offset:0x1c00
	s_nop 0
	v_mfma_f32_32x32x16_bf16 v[16:31], v[168:171], v[40:43], v[16:31]
	ds_read_b64_tr_b16 v[56:57], v137 offset:0x2400
	ds_read_b64_tr_b16 v[58:59], v137 offset:0x2c00
	ds_read_b64_tr_b16 v[60:61], v137 offset:0x3400
	ds_read_b64_tr_b16 v[62:63], v137 offset:0x3c00
	s_waitcnt lgkmcnt(6)
	s_nop 0
	v_mfma_f32_32x32x16_bf16 v[32:47], v[48:51], v[32:35], 0
	s_waitcnt lgkmcnt(4)
	s_nop 0
	v_mfma_f32_32x32x16_bf16 v[32:47], v[160:163], v[52:55], v[32:47]
	s_waitcnt lgkmcnt(2)
	s_nop 0
	v_mfma_f32_32x32x16_bf16 v[32:47], v[164:167], v[56:59], v[32:47]
	s_waitcnt lgkmcnt(0)
	ds_read_b64_tr_b16 v[52:53], v137 offset:0x600
	ds_read_b64_tr_b16 v[54:55], v137 offset:0xe00
	ds_read_b64_tr_b16 v[172:173], v137 offset:0x1600
	ds_read_b64_tr_b16 v[174:175], v137 offset:0x1e00
	s_nop 0
	v_mfma_f32_32x32x16_bf16 v[32:47], v[168:171], v[60:63], v[32:47]
	ds_read_b64_tr_b16 v[176:177], v137 offset:0x2600
	ds_read_b64_tr_b16 v[178:179], v137 offset:0x2e00
	ds_read_b64_tr_b16 v[180:181], v137 offset:0x3600
	ds_read_b64_tr_b16 v[182:183], v137 offset:0x3e00
	s_waitcnt lgkmcnt(6)
	s_nop 0
	v_mfma_f32_32x32x16_bf16 v[48:63], v[48:51], v[52:55], 0
	s_waitcnt lgkmcnt(4)
	s_nop 0
	v_mfma_f32_32x32x16_bf16 v[48:63], v[160:163], v[172:175], v[48:63]
	s_waitcnt lgkmcnt(2)
	s_nop 0
	v_mfma_f32_32x32x16_bf16 v[48:63], v[164:167], v[176:179], v[48:63]
	s_waitcnt lgkmcnt(0)
	v_max_f32_e32 v140, v81, v81
	v_max_f32_e32 v159, v80, v80
	v_max_f32_e32 v140, v159, v140
	v_max3_f32 v140, v140, v82, v83
	v_max3_f32 v140, v140, v84, v85
	v_max3_f32 v140, v140, v86, v87
	v_max3_f32 v140, v140, v88, v89
	v_max3_f32 v140, v140, v90, v91
	v_max3_f32 v140, v140, v92, v93
	v_max3_f32 v140, v140, v94, v95
	v_max3_f32 v140, v140, v64, v65
	v_max3_f32 v140, v140, v66, v67
	v_max3_f32 v140, v140, v68, v69
	v_max3_f32 v140, v140, v70, v71
	v_max3_f32 v140, v140, v72, v73
	v_max3_f32 v140, v140, v74, v75
	v_max3_f32 v140, v140, v76, v77
	v_max3_f32 v140, v140, v78, v79
	v_mov_b32_e32 v159, v140
	s_nop 1
	v_permlane32_swap_b32_e32 v140, v159
	v_max_f32_e32 v159, v159, v159
	v_max_f32_e32 v140, v140, v140
	v_max_f32_e32 v140, v140, v159
	v_sub_f32_e32 v159, v140, v158
	v_cmp_ge_f32_e32 vcc, s44, v159
	v_max_f32_e32 v159, v158, v140
	v_mfma_f32_32x32x16_bf16 v[48:63], v[168:171], v[180:183], v[48:63]
	v_sub_f32_e32 v140, v158, v159
	v_mul_f32_e32 v140, 0x3e0293ee, v140
	v_exp_f32_e32 v140, v140
	s_cmp_eq_u64 vcc, exec
	s_cselect_b64 s[44:45], -1, 0
	s_mov_b32 s33, 0x42b504f3
	v_cndmask_b32_e64 v140, v140, 1.0, s[44:45]
	v_cmp_gt_f32_e32 vcc, 1.0, v140
	s_cbranch_vccz .LBB0_71
	s_and_saveexec_b64 s[12:13], s[42:43]
	ds_write_b32 v136, v140 offset:128
	s_or_b64 exec, exec, s[12:13]
	s_waitcnt lgkmcnt(0)
	v_add_u32_e32 v172, s38, v184
	ds_read_b128 v[160:163], v172 offset:224
	ds_read_b128 v[164:167], v172 offset:192
	ds_read_b128 v[168:171], v172 offset:160
	ds_read_b128 v[172:175], v172 offset:128
	s_waitcnt lgkmcnt(0)
	v_pk_mul_f32 v[12:13], v[12:13], v[160:161]
	v_pk_mul_f32 v[8:9], v[8:9], v[164:165]
	v_pk_mul_f32 v[4:5], v[4:5], v[168:169]
	v_pk_mul_f32 v[14:15], v[14:15], v[162:163]
	v_pk_mul_f32 v[10:11], v[10:11], v[166:167]
	v_pk_mul_f32 v[6:7], v[6:7], v[170:171]
	v_pk_mul_f32 v[2:3], v[2:3], v[174:175]
	v_pk_mul_f32 v[0:1], v[0:1], v[172:173]
	v_pk_mul_f32 v[28:29], v[28:29], v[160:161]
	v_pk_mul_f32 v[24:25], v[24:25], v[164:165]
	v_pk_mul_f32 v[20:21], v[20:21], v[168:169]
	v_pk_mul_f32 v[30:31], v[30:31], v[162:163]
	v_pk_mul_f32 v[26:27], v[26:27], v[166:167]
	v_pk_mul_f32 v[22:23], v[22:23], v[170:171]
	v_pk_mul_f32 v[18:19], v[18:19], v[174:175]
	v_pk_mul_f32 v[16:17], v[16:17], v[172:173]
	v_pk_mul_f32 v[44:45], v[44:45], v[160:161]
	v_pk_mul_f32 v[40:41], v[40:41], v[164:165]
	v_pk_mul_f32 v[36:37], v[36:37], v[168:169]
	v_pk_mul_f32 v[46:47], v[46:47], v[162:163]
	v_pk_mul_f32 v[42:43], v[42:43], v[166:167]
	v_pk_mul_f32 v[38:39], v[38:39], v[170:171]
	v_pk_mul_f32 v[34:35], v[34:35], v[174:175]
	v_pk_mul_f32 v[32:33], v[32:33], v[172:173]
	v_pk_mul_f32 v[60:61], v[60:61], v[160:161]
	v_pk_mul_f32 v[56:57], v[56:57], v[164:165]
	v_pk_mul_f32 v[52:53], v[52:53], v[168:169]
	v_pk_mul_f32 v[62:63], v[62:63], v[162:163]
	v_pk_mul_f32 v[58:59], v[58:59], v[166:167]
	v_pk_mul_f32 v[54:55], v[54:55], v[170:171]
	v_pk_mul_f32 v[50:51], v[50:51], v[174:175]
	v_pk_mul_f32 v[48:49], v[48:49], v[172:173]
